# diff-attn loop: first four V fragment read pairs of each PV issued during the preceding QK segment (as their K temp buffers retire)
# baseline (speedup 1.0000x reference)
; __device__ __forceinline__ void finishSM(f32x16& p0, f32x16& p1, float alpha, float& l_reg, bf16x8& pa0, bf16x8& pa1, bf16x8& pa2, bf16x8& pa3) {
;     for (int r = 0; r < 16; ++r) p1[r] = __builtin_amdgcn_exp2f(p1[r]);
;     float ps = 0; for (int r = 0; r < 16; ++r) ps += p0[r]; for (int r = 0; r < 16; ++r) ps += p1[r];
;     { auto rr = __builtin_amdgcn_permlane32_swap(__float_as_uint(ps), __float_as_uint(ps), false, false);
;       ps = __uint_as_float(rr[0]) + __uint_as_float(rr[1]); }
;     l_reg = l_reg * alpha + ps;
;     ...
;     PK4(p0, 0, pa0); PK4(p0, 8, pa1); PK4(p1, 0, pa2); PK4(p1, 8, pa3);
;     ...
; }
; template <int KB, bool SK>
; __device__ __forceinline__ void qkt(f32x16& p0, f32x16& p1, const char* K_lds, int r32, int hi, const bf16x8* qr, bool act) {
;     if (SK && !act) { const float NEG = -__builtin_inff();
; #pragma unroll
;         for (int r = 0; r < 16; ++r) { p0[r] = NEG; p1[r] = NEG; } return; }
;     p0 = f32x16{}; p1 = f32x16{};
;     const char* kb[4];
; #pragma unroll
;     for (int dd = 0; dd < 4; ++dd) kb[dd] = K_lds + KB * SHM_K + KSWZ(r32, (dd * 16 + hi * 8) * 2);
; #pragma unroll
;     for (int d0 = 0; d0 < 8; ++d0) { const char* a = kb[d0 & 3] + (d0 >> 2) * 128;
;         bf16x8 b0 = *reinterpret_cast<const bf16x8*>(a);
;         bf16x8 b1 = *reinterpret_cast<const bf16x8*>(a + 32 * 256);
;         const bf16x8 qf = qr[d0];
;         p0 = __builtin_amdgcn_mfma_f32_32x32x16_bf16(b0, qf, p0, 0, 0, 0);
;         p1 = __builtin_amdgcn_mfma_f32_32x32x16_bf16(b1, qf, p1, 0, 0, 0); }
; }
; template <int VB, bool SK>
; __device__ __forceinline__ void pv_tile(f32x16* o, int vb0, bf16x8 pa0, bf16x8 pa1, bf16x8 pa2, bf16x8 pa3, bool act) {
;     if (SK && !act) return;
;     ...
;     PV_D0(0); PV_D0(1); PV_D0(2); PV_D0(3);
.Lattn_prio_skip:
.LBB0_1129:
	ds_read_b128 v[182:185], v211 offset:49152
	ds_read_b128 v[186:189], v211 offset:57344
	ds_read_b128 v[190:193], v212 offset:49152
	ds_read_b128 v[228:231], v212 offset:57344
	ds_read_b128 v[232:235], v213 offset:49152
	ds_read_b128 v[236:239], v213 offset:57344
	ds_read_b128 v[240:243], v214 offset:49152
	ds_read_b128 v[244:247], v214 offset:57344
	v_exp_f32_e32 v126, v126
	v_exp_f32_e32 v127, v127
	v_exp_f32_e32 v124, v124
	v_exp_f32_e32 v125, v125
	v_exp_f32_e32 v120, v120
	v_exp_f32_e32 v121, v121
	s_add_i32 s4, s26, 0xffffff81
	s_sub_i32 s5, s26, 64
	s_waitcnt lgkmcnt(7)
	v_mfma_f32_32x32x16_bf16 v[86:101], v[182:185], v[158:161], 0
	ds_read_b128 v[182:185], v211 offset:49280
	v_exp_f32_e32 v116, v116
	v_exp_f32_e32 v117, v117
	v_exp_f32_e32 v114, v114
	v_exp_f32_e32 v115, v115
	v_exp_f32_e32 v128, v128
	s_waitcnt lgkmcnt(7)
	v_mfma_f32_32x32x16_bf16 v[70:85], v[186:189], v[158:161], 0
	ds_read_b128 v[186:189], v211 offset:57472
	v_exp_f32_e32 v129, v129
	v_exp_f32_e32 v122, v122
	v_exp_f32_e32 v123, v123
	v_exp_f32_e32 v118, v118
	v_exp_f32_e32 v119, v119
	s_waitcnt lgkmcnt(7)
	v_mfma_f32_32x32x16_bf16 v[86:101], v[190:193], v[154:157], v[86:101]
	ds_read_b128 v[190:193], v212 offset:49280
	v_add_f32_e32 v179, 0, v170
	v_add_f32_e32 v179, v171, v179
	v_add_f32_e32 v179, v172, v179
	v_add_f32_e32 v179, v173, v179
	v_add_f32_e32 v179, v174, v179
	s_waitcnt lgkmcnt(7)
	v_mfma_f32_32x32x16_bf16 v[70:85], v[228:231], v[154:157], v[70:85]
	ds_read_b128 v[228:231], v212 offset:57472
	v_add_f32_e32 v179, v176, v179
	v_add_f32_e32 v179, v175, v179
	v_add_f32_e32 v179, v177, v179
	v_add_f32_e32 v179, v162, v179
	v_add_f32_e32 v179, v163, v179
	s_waitcnt lgkmcnt(7)
	v_mfma_f32_32x32x16_bf16 v[86:101], v[232:235], v[150:153], v[86:101]
	ds_read_b128 v[232:235], v213 offset:49280
	v_add_f32_e32 v110, v164, v179
	v_add_f32_e32 v110, v166, v110
	v_add_f32_e32 v110, v165, v110
	v_add_f32_e32 v110, v167, v110
	s_waitcnt lgkmcnt(7)
	v_mfma_f32_32x32x16_bf16 v[70:85], v[236:239], v[150:153], v[70:85]
	ds_read_b128 v[236:239], v213 offset:57472
	v_add_f32_e32 v110, v168, v110
	v_add_f32_e32 v110, v169, v110
	v_add_f32_e32 v110, v126, v110
	v_add_f32_e32 v102, v127, v110
	s_waitcnt lgkmcnt(7)
	v_mfma_f32_32x32x16_bf16 v[86:101], v[240:243], v[134:137], v[86:101]
	ds_read_b128 v[240:243], v214 offset:49280
	v_add_f32_e32 v102, v124, v102
	v_add_f32_e32 v102, v125, v102
	v_add_f32_e32 v102, v120, v102
	v_add_f32_e32 v102, v121, v102
	s_waitcnt lgkmcnt(7)
	v_mfma_f32_32x32x16_bf16 v[70:85], v[244:247], v[134:137], v[70:85]
	ds_read_b128 v[244:247], v214 offset:57472
	v_add_f32_e32 v102, v116, v102
	v_add_f32_e32 v102, v117, v102
	v_add_f32_e32 v102, v114, v102
	v_add_f32_e32 v102, v115, v102
	s_waitcnt lgkmcnt(7)
	v_mfma_f32_32x32x16_bf16 v[86:101], v[182:185], v[138:141], v[86:101]
	ds_read_b64_tr_b16 v[182:183], v202 offset:0x0
	ds_read_b64_tr_b16 v[184:185], v202 offset:0x800
	v_add_f32_e32 v102, v128, v102
	v_add_f32_e32 v102, v129, v102
	v_add_f32_e32 v102, v122, v102
	v_add_f32_e32 v102, v123, v102
	s_waitcnt lgkmcnt(8)
	v_mfma_f32_32x32x16_bf16 v[70:85], v[186:189], v[138:141], v[70:85]
	ds_read_b64_tr_b16 v[186:187], v202 offset:0x1000
	ds_read_b64_tr_b16 v[188:189], v202 offset:0x1800
	v_add_f32_e32 v102, v118, v102
	v_add_f32_e32 v223, v119, v102
	v_mov_b32_e32 v224, v223
	s_nop 1
	v_permlane32_swap_b32_e32 v223, v224
	s_waitcnt lgkmcnt(9)
	v_mfma_f32_32x32x16_bf16 v[86:101], v[190:193], v[142:145], v[86:101]
	ds_read_b64_tr_b16 v[190:191], v202 offset:0x2000
	ds_read_b64_tr_b16 v[192:193], v202 offset:0x2800
	v_cvt_pk_bf16_f32 v102, v170, v171
	v_cvt_pk_bf16_f32 v103, v172, v173
	v_cvt_pk_bf16_f32 v104, v174, v176
	v_cvt_pk_bf16_f32 v105, v175, v177
	s_waitcnt lgkmcnt(10)
	v_mfma_f32_32x32x16_bf16 v[70:85], v[228:231], v[142:145], v[70:85]
	v_cvt_pk_bf16_f32 v66, v162, v163
	v_cvt_pk_bf16_f32 v67, v164, v166
	v_cvt_pk_bf16_f32 v68, v165, v167
	v_cvt_pk_bf16_f32 v69, v168, v169
	s_waitcnt lgkmcnt(9)
	v_mfma_f32_32x32x16_bf16 v[86:101], v[232:235], v[146:149], v[86:101]
	v_cvt_pk_bf16_f32 v106, v126, v127
	v_cvt_pk_bf16_f32 v107, v124, v125
	v_cvt_pk_bf16_f32 v108, v120, v121
	v_cvt_pk_bf16_f32 v109, v116, v117
	s_waitcnt lgkmcnt(8)
	v_mfma_f32_32x32x16_bf16 v[70:85], v[236:239], v[146:149], v[70:85]
	v_cvt_pk_bf16_f32 v110, v114, v115
	v_cvt_pk_bf16_f32 v111, v128, v129
	v_cvt_pk_bf16_f32 v112, v122, v123
	v_cvt_pk_bf16_f32 v113, v118, v119
	s_waitcnt lgkmcnt(7)
	v_mfma_f32_32x32x16_bf16 v[86:101], v[240:243], v[130:133], v[86:101]
	s_nop 1
	v_permlane32_swap_b32_e32 v102, v104
	v_permlane32_swap_b32_e32 v103, v105
	v_permlane32_swap_b32_e32 v66, v68
	v_permlane32_swap_b32_e32 v67, v69
	s_waitcnt lgkmcnt(6)
	v_mfma_f32_32x32x16_bf16 v[70:85], v[244:247], v[130:133], v[70:85]
	ds_read_b64_tr_b16 v[244:245], v202 offset:0x3000
	ds_read_b64_tr_b16 v[246:247], v202 offset:0x3800
	v_permlane32_swap_b32_e32 v106, v108
	v_permlane32_swap_b32_e32 v107, v109
	v_permlane32_swap_b32_e32 v110, v112
	v_permlane32_swap_b32_e32 v111, v113
	v_add_u32_e32 v114, 0x2000, v255
	global_load_dwordx4 v[162:165], v255, s[42:43]
	global_load_dwordx4 v[166:169], v114, s[42:43]
	global_load_dwordx4 v[170:173], v255, s[22:23]
	global_load_dwordx4 v[174:177], v114, s[22:23]
	s_cmp_le_i32 s5, s13
	s_cselect_b64 s[52:53], -1, 0
	s_cmp_gt_i32 s4, s15
	s_cselect_b64 s[4:5], -1, 0
	s_and_b64 s[4:5], s[52:53], s[4:5]
	s_and_b64 vcc, exec, s[4:5]
	ds_read_b64_tr_b16 v[114:115], v202 offset:0x200
	ds_read_b64_tr_b16 v[116:117], v202 offset:0xa00
	ds_read_b64_tr_b16 v[118:119], v202 offset:0x1200
	ds_read_b64_tr_b16 v[120:121], v202 offset:0x1a00
	ds_read_b64_tr_b16 v[122:123], v202 offset:0x2200
	ds_read_b64_tr_b16 v[124:125], v202 offset:0x2a00
	s_cbranch_vccnz .Lh1_nomask
; __device__ __forceinline__ void mask_tile(f32x16& p0, f32x16& p1, int dq, unsigned W) {
;     const float NEG = -__builtin_inff();
; #pragma unroll
;     for (int r = 0; r < 16; ++r) {
;         const int c = (r & 3) + 8 * (r >> 2);
;         if ((unsigned)(dq - c) >= W) p0[r] = NEG;
;         if ((unsigned)(dq - c - 32) >= W) p1[r] = NEG;
;     }
; }
; __device__ __forceinline__ void partialSM(f32x16& p0, f32x16& p1, float& m_reg, float& mn, float& alpha) {
;     float pmax = p0[0]; for (int r = 1; r < 16; ++r) pmax = fmaxf(pmax, p0[r]); for (int r = 0; r < 16; ++r) pmax = fmaxf(pmax, p1[r]);
;     { auto rr = __builtin_amdgcn_permlane32_swap(__float_as_uint(pmax), __float_as_uint(pmax), false, false);
;       pmax = fmaxf(__uint_as_float(rr[0]), __uint_as_float(rr[1])); }
;     constexpr float C2 = 1.4426950408889634f * SCALE;
;     if (__builtin_expect(__all((pmax - m_reg) * SCALE <= THR), 1)) { mn = m_reg; alpha = 1.f; }
;     else { mn = fmaxf(m_reg, pmax); alpha = __builtin_amdgcn_exp2f((m_reg - mn) * C2); m_reg = mn; }
; template <int VB, bool SK>
; __device__ __forceinline__ void pv_tile(f32x16* o, int vb0, bf16x8 pa0, bf16x8 pa1, bf16x8 pa2, bf16x8 pa3, bool act) {
;     ...
;     PV_D0(0); PV_D0(1); PV_D0(2); PV_D0(3);
	v_add_u32_e32 v226, s80, v222
	v_subrev_u32_e32 v240, 64, v226
	v_cmp_gt_u32_e32 vcc, s85, v240
	v_add_u32_e32 v240, 0xffffffa0, v226
	s_nop 0
	v_cndmask_b32_e32 v86, v215, v86, vcc
	v_cmp_gt_u32_e32 vcc, s85, v240
	v_add_u32_e32 v240, 0xffffffbf, v226
	s_nop 0
	v_cndmask_b32_e32 v70, v215, v70, vcc
	v_cmp_gt_u32_e32 vcc, s85, v240
	v_add_u32_e32 v240, 0xffffff9f, v226
	s_nop 0
	v_cndmask_b32_e32 v87, v215, v87, vcc
	v_cmp_gt_u32_e32 vcc, s85, v240
	v_add_u32_e32 v240, 0xffffffbe, v226
	s_nop 0
	v_cndmask_b32_e32 v71, v215, v71, vcc
	v_cmp_gt_u32_e32 vcc, s85, v240
	v_add_u32_e32 v240, 0xffffff9e, v226
	s_nop 0
	v_cndmask_b32_e32 v88, v215, v88, vcc
	v_cmp_gt_u32_e32 vcc, s85, v240
	v_add_u32_e32 v240, 0xffffffbd, v226
	s_nop 0
	v_cndmask_b32_e32 v72, v215, v72, vcc
	v_cmp_gt_u32_e32 vcc, s85, v240
	v_add_u32_e32 v240, 0xffffff9d, v226
	s_nop 0
	v_cndmask_b32_e32 v89, v215, v89, vcc
	v_cmp_gt_u32_e32 vcc, s85, v240
	v_add_u32_e32 v240, 0xffffffb8, v226
	s_nop 0
	v_cndmask_b32_e32 v73, v215, v73, vcc
	v_cmp_gt_u32_e32 vcc, s85, v240
	v_add_u32_e32 v240, 0xffffff98, v226
	s_nop 0
	v_cndmask_b32_e32 v90, v215, v90, vcc
	v_cmp_gt_u32_e32 vcc, s85, v240
	v_add_u32_e32 v240, 0xffffffb7, v226
	s_nop 0
	v_cndmask_b32_e32 v74, v215, v74, vcc
	v_cmp_gt_u32_e32 vcc, s85, v240
	v_add_u32_e32 v240, 0xffffff97, v226
	s_nop 0
	v_cndmask_b32_e32 v91, v215, v91, vcc
	v_cmp_gt_u32_e32 vcc, s85, v240
	v_add_u32_e32 v240, 0xffffffb6, v226
	s_nop 0
	v_cndmask_b32_e32 v75, v215, v75, vcc
	v_cmp_gt_u32_e32 vcc, s85, v240
	v_add_u32_e32 v240, 0xffffff96, v226
	s_nop 0
	v_cndmask_b32_e32 v92, v215, v92, vcc
	v_cmp_gt_u32_e32 vcc, s85, v240
	v_add_u32_e32 v240, 0xffffffb5, v226
	s_nop 0
	v_cndmask_b32_e32 v76, v215, v76, vcc
	v_cmp_gt_u32_e32 vcc, s85, v240
	v_add_u32_e32 v240, 0xffffff95, v226
	s_nop 0
	v_cndmask_b32_e32 v93, v215, v93, vcc
	v_cmp_gt_u32_e32 vcc, s85, v240
	v_add_u32_e32 v240, 0xffffffb0, v226
	s_nop 0
	v_cndmask_b32_e32 v77, v215, v77, vcc
	v_cmp_gt_u32_e32 vcc, s85, v240
	v_add_u32_e32 v240, 0xffffff90, v226
	s_nop 0
	v_cndmask_b32_e32 v94, v215, v94, vcc
	v_cmp_gt_u32_e32 vcc, s85, v240
	v_add_u32_e32 v240, 0xffffffaf, v226
	s_nop 0
	v_cndmask_b32_e32 v78, v215, v78, vcc
	v_cmp_gt_u32_e32 vcc, s85, v240
	v_add_u32_e32 v240, 0xffffff8f, v226
	s_nop 0
	v_cndmask_b32_e32 v95, v215, v95, vcc
	v_cmp_gt_u32_e32 vcc, s85, v240
	v_add_u32_e32 v240, 0xffffffae, v226
	s_nop 0
	v_cndmask_b32_e32 v79, v215, v79, vcc
	v_cmp_gt_u32_e32 vcc, s85, v240
	v_add_u32_e32 v240, 0xffffff8e, v226
	s_nop 0
	v_cndmask_b32_e32 v96, v215, v96, vcc
	v_cmp_gt_u32_e32 vcc, s85, v240
	v_add_u32_e32 v240, 0xffffffad, v226
	s_nop 0
	v_cndmask_b32_e32 v80, v215, v80, vcc
	v_cmp_gt_u32_e32 vcc, s85, v240
	v_add_u32_e32 v240, 0xffffff8d, v226
	s_nop 0
	v_cndmask_b32_e32 v97, v215, v97, vcc
	v_cmp_gt_u32_e32 vcc, s85, v240
	v_add_u32_e32 v240, 0xffffffa8, v226
	s_nop 0
	v_cndmask_b32_e32 v81, v215, v81, vcc
	v_cmp_gt_u32_e32 vcc, s85, v240
	v_add_u32_e32 v240, 0xffffff88, v226
	s_nop 0
	v_cndmask_b32_e32 v98, v215, v98, vcc
	v_cmp_gt_u32_e32 vcc, s85, v240
	v_add_u32_e32 v240, 0xffffffa7, v226
	s_nop 0
	v_cndmask_b32_e32 v82, v215, v82, vcc
	v_cmp_gt_u32_e32 vcc, s85, v240
	v_add_u32_e32 v240, 0xffffff87, v226
	s_nop 0
	v_cndmask_b32_e32 v99, v215, v99, vcc
	v_cmp_gt_u32_e32 vcc, s85, v240
	v_add_u32_e32 v240, 0xffffffa6, v226
	s_nop 0
	v_cndmask_b32_e32 v83, v215, v83, vcc
	v_cmp_gt_u32_e32 vcc, s85, v240
	v_add_u32_e32 v240, 0xffffff86, v226
	s_nop 0
	v_cndmask_b32_e32 v100, v215, v100, vcc
	v_cmp_gt_u32_e32 vcc, s85, v240
	v_add_u32_e32 v240, 0xffffffa5, v226
	s_nop 0
	v_cndmask_b32_e32 v84, v215, v84, vcc
	v_cmp_gt_u32_e32 vcc, s85, v240
	v_add_u32_e32 v240, 0xffffff85, v226
	s_nop 0
	v_cndmask_b32_e32 v101, v215, v101, vcc
	v_cmp_gt_u32_e32 vcc, s85, v240
	s_nop 1
	v_cndmask_b32_e32 v85, v215, v85, vcc
.Lh1_nomask:
	v_max_f32_e32 v240, v86, v87
	v_max3_f32 v240, v240, v88, v89
	v_max3_f32 v240, v240, v90, v91
	v_max3_f32 v240, v240, v92, v93
	v_max3_f32 v240, v240, v94, v95
	s_waitcnt lgkmcnt(12)
	v_mfma_f32_32x32x16_bf16 v[34:49], v[102:105], v[182:185], v[34:49]
	ds_read_b64_tr_b16 v[126:127], v202 offset:0x3200
	ds_read_b64_tr_b16 v[128:129], v202 offset:0x3a00
	v_max3_f32 v240, v240, v96, v97
	v_max3_f32 v240, v240, v98, v99
	v_max3_f32 v240, v240, v100, v101
	v_max3_f32 v240, v240, v70, v71
	s_waitcnt lgkmcnt(12)
	v_mfma_f32_32x32x16_bf16 v[34:49], v[66:69], v[186:189], v[34:49]
	ds_read_b64_tr_b16 v[182:183], v202 offset:0x400
	ds_read_b64_tr_b16 v[184:185], v202 offset:0xc00
	v_max3_f32 v240, v240, v72, v73
	v_max3_f32 v240, v240, v74, v75
	v_max3_f32 v240, v240, v76, v77
	v_max3_f32 v240, v240, v78, v79
	s_waitcnt lgkmcnt(12)
	v_mfma_f32_32x32x16_bf16 v[34:49], v[106:109], v[190:193], v[34:49]
	ds_read_b64_tr_b16 v[186:187], v202 offset:0x1400
	ds_read_b64_tr_b16 v[188:189], v202 offset:0x1c00
	v_max3_f32 v240, v240, v80, v81
	v_max3_f32 v240, v240, v82, v83
	v_max3_f32 v240, v240, v84, v85
	v_mov_b32_e32 v241, v240
	s_waitcnt lgkmcnt(12)
	v_mfma_f32_32x32x16_bf16 v[34:49], v[110:113], v[244:247], v[34:49]
	ds_read_b64_tr_b16 v[190:191], v202 offset:0x2400
	ds_read_b64_tr_b16 v[192:193], v202 offset:0x2c00
	s_nop 1
	v_permlane32_swap_b32_e32 v240, v241
	v_max_f32_e32 v240, v240, v241
	v_sub_f32_e32 v241, v240, v252
	v_mul_f32_e32 v241, 0x3db504f3, v241
	s_waitcnt lgkmcnt(12)
	v_mfma_f32_32x32x16_bf16 v[50:65], v[102:105], v[114:117], v[50:65]
	ds_read_b64_tr_b16 v[244:245], v202 offset:0x3400
	ds_read_b64_tr_b16 v[246:247], v202 offset:0x3c00
	v_cmp_ge_f32_e32 vcc, s86, v241
	s_cmp_eq_u64 vcc, exec
	s_cselect_b64 s[4:5], -1, 0
	v_mov_b32_e32 v225, 1.0
	s_cbranch_scc0 .Lh1_rare
; #define SBAR() __builtin_amdgcn_sched_barrier(0)
; #define VMW() asm volatile("s_waitcnt vmcnt(0)" ::: "memory")
; #define SLOAD_H(Kp, Vp, k0) do { S.st_v0 = load8<TIn>(ROW(Vp, k0, sr)); S.st_v1 = load8<TIn>(ROW(Vp, k0, 32 + sr));              \
;                          S.st_k0 = load8<TIn>(ROW(Kp, k0, sr)); S.st_k1 = load8<TIn>(ROW(Kp, k0, 32 + sr)); } while (0)
; #define SWRITE_HV(bf) do { *(bf16x8*)(V_lds + (bf) * SHM_V + vst0) = S.st_v0; *(bf16x8*)(V_lds + (bf) * SHM_V + vst1) = S.st_v1; } while (0)
; #define SWRITE_H(bf) do { SWRITE_HV(bf); SWRITE_HK(bf); } while (0)
; #define SLOAD_F(p, k0) do { S.sf0 = *(const f32x4*)ROW(p, k0, sr); S.sf1 = *(const f32x4*)(ROW(p, k0, sr) + 4);                \
;                             S.sf2 = *(const f32x4*)ROW(p, k0, 32 + sr); S.sf3 = *(const f32x4*)(ROW(p, k0, 32 + sr) + 4); } while (0)
; #define SWRITE_KF(bf) do { *(bf16x8*)(K_lds + (bf) * SHM_K + kws) = pack8(S.sf0, S.sf1); *(bf16x8*)(K_lds + (bf) * SHM_K + kws + 32 * 256) = pack8(S.sf2, S.sf3); } while (0)
; #define SWRITE_VF(bf) do { *(bf16x8*)(V_lds + (bf) * SHM_V + vst0) = pack8(S.sf0, S.sf1); *(bf16x8*)(V_lds + (bf) * SHM_V + vst1) = pack8(S.sf2, S.sf3); } while (0)
; template <int VB, bool SK>
; __device__ __forceinline__ void pv_tile(f32x16* o, int vb0, bf16x8 pa0, bf16x8 pa1, bf16x8 pa2, bf16x8 pa3, bool act) {
;     ...
;     PV_D0(0); PV_D0(1); PV_D0(2); PV_D0(3);
; template <class TIn, class TOut>
; __device__ __forceinline__ void causal_swa_block(const BlockRef<TIn, TOut>& cur, const BlockRef<TIn, TOut>& nxt, int skv, int W, char* lds, Seam<TIn>& S) {
;     ...
;     constexpr int NQL = F32 ? 16 : 8;
;     constexpr bool SK = WSKIP && !F32;
;     ...
;     f32x16 pA0, pA1, pB0, pB1; float mnA, mnB, alA, alB; bf16x8 pa0, pa1, pa2, pa3;
;     if constexpr (F32) { VMW(); SWRITE_VF(0); SBAR(); } else { SWRITE_HV(0); SBAR(); }
;     if (NT > 1) { if constexpr (F32) SLOAD_F((const float*)Kh, KBASE(1)); else SLOAD_H(Kh, Vh, KBASE(1)); }
;     SBAR(); qkt<0, SK>(pA0, pA1, K_lds, r32, hi, S.qr, ACT(0));
;     if constexpr (F32) { if (NT > 1) { VMW(); SWRITE_KF(1); SBAR(); SLOAD_F((const float*)Vh, KBASE(1)); } }
;     MASKT(pA0, pA1, 0); partialSM(pA0, pA1, m_reg, mnA, alA);
;     if (NT > 1) { VMW(); if constexpr (F32) { SWRITE_VF(1); SBAR(); if (NT > 2) SLOAD_F((const float*)Kh, KBASE(2)); } else SWRITE_H(1); }
;     __syncthreads();
.Lh1_back:
	v_fmamk_f32 v228, v86, 0x3e0293ee, v253
	v_fmamk_f32 v229, v87, 0x3e0293ee, v253
	s_waitcnt lgkmcnt(12)
	v_mfma_f32_32x32x16_bf16 v[50:65], v[66:69], v[118:121], v[50:65]
	ds_read_b64_tr_b16 v[114:115], v202 offset:0x600
	ds_read_b64_tr_b16 v[116:117], v202 offset:0xe00
	v_fmamk_f32 v230, v88, 0x3e0293ee, v253
	v_fmamk_f32 v231, v89, 0x3e0293ee, v253
	v_fmamk_f32 v232, v90, 0x3e0293ee, v253
	s_waitcnt lgkmcnt(12)
	v_mfma_f32_32x32x16_bf16 v[50:65], v[106:109], v[122:125], v[50:65]
	ds_read_b64_tr_b16 v[118:119], v202 offset:0x1600
	ds_read_b64_tr_b16 v[120:121], v202 offset:0x1e00
	v_fmamk_f32 v233, v91, 0x3e0293ee, v253
	v_fmamk_f32 v234, v92, 0x3e0293ee, v253
	v_fmamk_f32 v235, v93, 0x3e0293ee, v253
	s_waitcnt lgkmcnt(12)
	v_mfma_f32_32x32x16_bf16 v[50:65], v[110:113], v[126:129], v[50:65]
	ds_read_b64_tr_b16 v[122:123], v202 offset:0x2600
	ds_read_b64_tr_b16 v[124:125], v202 offset:0x2e00
	v_fmamk_f32 v236, v94, 0x3e0293ee, v253
	v_fmamk_f32 v237, v95, 0x3e0293ee, v253
	v_fmamk_f32 v238, v96, 0x3e0293ee, v253
	s_waitcnt lgkmcnt(12)
	v_mfma_f32_32x32x16_bf16 v[18:33], v[102:105], v[182:185], v[18:33]
	ds_read_b64_tr_b16 v[126:127], v202 offset:0x3600
	ds_read_b64_tr_b16 v[128:129], v202 offset:0x3e00
	v_fmamk_f32 v239, v97, 0x3e0293ee, v253
	v_fmamk_f32 v98, v98, 0x3e0293ee, v253
	v_fmamk_f32 v99, v99, 0x3e0293ee, v253
	s_waitcnt lgkmcnt(12)
	v_mfma_f32_32x32x16_bf16 v[18:33], v[66:69], v[186:189], v[18:33]
	v_fmamk_f32 v100, v100, 0x3e0293ee, v253
	v_fmamk_f32 v101, v101, 0x3e0293ee, v253
	v_fmamk_f32 v86, v70, 0x3e0293ee, v253
	s_waitcnt lgkmcnt(10)
	v_mfma_f32_32x32x16_bf16 v[18:33], v[106:109], v[190:193], v[18:33]
	v_fmamk_f32 v95, v71, 0x3e0293ee, v253
	v_fmamk_f32 v96, v72, 0x3e0293ee, v253
	v_fmamk_f32 v97, v73, 0x3e0293ee, v253
	s_waitcnt lgkmcnt(8)
	v_mfma_f32_32x32x16_bf16 v[18:33], v[110:113], v[244:247], v[18:33]
	v_fmamk_f32 v179, v74, 0x3e0293ee, v253
	v_fmamk_f32 v87, v75, 0x3e0293ee, v253
	v_fmamk_f32 v88, v76, 0x3e0293ee, v253
	s_waitcnt lgkmcnt(0)
	s_barrier
	s_waitcnt vmcnt(0)
	v_mfma_f32_32x32x16_bf16 v[2:17], v[102:105], v[114:117], v[2:17]
	ds_write_b128 v209, v[162:165]
	v_fmamk_f32 v89, v77, 0x3e0293ee, v253
	v_fmamk_f32 v90, v78, 0x3e0293ee, v253
	v_fmamk_f32 v91, v79, 0x3e0293ee, v253
	v_mfma_f32_32x32x16_bf16 v[2:17], v[66:69], v[118:121], v[2:17]
	ds_write_b128 v210, v[166:169]
	v_fmamk_f32 v92, v80, 0x3e0293ee, v253
	v_fmamk_f32 v93, v81, 0x3e0293ee, v253
	v_fmamk_f32 v94, v82, 0x3e0293ee, v253
	v_mfma_f32_32x32x16_bf16 v[2:17], v[106:109], v[122:125], v[2:17]
	ds_write_b128 v217, v[170:173] offset:32768
	v_fmamk_f32 v180, v83, 0x3e0293ee, v253
	v_fmamk_f32 v181, v84, 0x3e0293ee, v253
	v_fmamk_f32 v178, v85, 0x3e0293ee, v253
	v_mfma_f32_32x32x16_bf16 v[2:17], v[110:113], v[126:129], v[2:17]
	ds_write_b128 v217, v[174:177] offset:40960
	s_and_b64 vcc, exec, s[4:5]
	s_cbranch_vccnz .Lh1_noresc
	s_and_saveexec_b64 s[52:53], s[0:1]
	ds_write_b32 v219, v225 offset:128
	s_or_b64 exec, exec, s[52:53]
	s_waitcnt lgkmcnt(0)
	ds_read_b128 v[102:105], v218 offset:224
	ds_read_b128 v[106:109], v218 offset:192
	ds_read_b128 v[110:113], v218 offset:160
	ds_read_b128 v[114:117], v218 offset:128
	s_waitcnt lgkmcnt(3)
	v_pk_mul_f32 v[48:49], v[48:49], v[104:105]
	s_waitcnt lgkmcnt(2)
	v_pk_mul_f32 v[44:45], v[44:45], v[108:109]
	s_waitcnt lgkmcnt(1)
	v_pk_mul_f32 v[40:41], v[40:41], v[112:113]
	s_waitcnt lgkmcnt(0)
	v_pk_mul_f32 v[36:37], v[36:37], v[116:117]
	v_pk_mul_f32 v[46:47], v[46:47], v[102:103]
	v_pk_mul_f32 v[42:43], v[42:43], v[106:107]
	v_pk_mul_f32 v[38:39], v[38:39], v[110:111]
	v_pk_mul_f32 v[34:35], v[34:35], v[114:115]
	v_pk_mul_f32 v[64:65], v[64:65], v[104:105]
	v_pk_mul_f32 v[60:61], v[60:61], v[108:109]
	v_pk_mul_f32 v[56:57], v[56:57], v[112:113]
	v_pk_mul_f32 v[52:53], v[52:53], v[116:117]
	v_pk_mul_f32 v[62:63], v[62:63], v[102:103]
	v_pk_mul_f32 v[58:59], v[58:59], v[106:107]
	v_pk_mul_f32 v[54:55], v[54:55], v[110:111]
	v_pk_mul_f32 v[50:51], v[50:51], v[114:115]
	v_pk_mul_f32 v[32:33], v[32:33], v[104:105]
	v_pk_mul_f32 v[28:29], v[28:29], v[108:109]
	v_pk_mul_f32 v[24:25], v[24:25], v[112:113]
	v_pk_mul_f32 v[20:21], v[20:21], v[116:117]
	v_pk_mul_f32 v[30:31], v[30:31], v[102:103]
	v_pk_mul_f32 v[26:27], v[26:27], v[106:107]
	v_pk_mul_f32 v[22:23], v[22:23], v[110:111]
	v_pk_mul_f32 v[18:19], v[18:19], v[114:115]
	v_pk_mul_f32 v[16:17], v[16:17], v[104:105]
	v_pk_mul_f32 v[12:13], v[12:13], v[108:109]
	v_pk_mul_f32 v[8:9], v[8:9], v[112:113]
	v_pk_mul_f32 v[4:5], v[4:5], v[116:117]
	v_pk_mul_f32 v[14:15], v[14:15], v[102:103]
	v_pk_mul_f32 v[10:11], v[10:11], v[106:107]
	v_pk_mul_f32 v[6:7], v[6:7], v[110:111]
	v_pk_mul_f32 v[2:3], v[2:3], v[114:115]
; __device__ __forceinline__ void partialSM(f32x16& p0, f32x16& p1, float& m_reg, float& mn, float& alpha) {
;     ...
;     for (int r = 0; r < 16; ++r) p0[r] = __builtin_amdgcn_exp2f(p0[r]);
; }
; __device__ __forceinline__ void finishSM(f32x16& p0, f32x16& p1, float alpha, float& l_reg, bf16x8& pa0, bf16x8& pa1, bf16x8& pa2, bf16x8& pa3) {
;     for (int r = 0; r < 16; ++r) p1[r] = __builtin_amdgcn_exp2f(p1[r]);
;     float ps = 0; for (int r = 0; r < 16; ++r) ps += p0[r]; for (int r = 0; r < 16; ++r) ps += p1[r];
;     { auto rr = __builtin_amdgcn_permlane32_swap(__float_as_uint(ps), __float_as_uint(ps), false, false);
;       ps = __uint_as_float(rr[0]) + __uint_as_float(rr[1]); }
;     l_reg = l_reg * alpha + ps;
;     ...
;     PK4(p0, 0, pa0); PK4(p0, 8, pa1); PK4(p1, 0, pa2); PK4(p1, 8, pa3);
; template <int KB, bool SK>
; __device__ __forceinline__ void qkt(f32x16& p0, f32x16& p1, const char* K_lds, int r32, int hi, const bf16x8* qr, bool act) {
;     ...
;     for (int d0 = 0; d0 < 8; ++d0) { const char* a = kb[d0 & 3] + (d0 >> 2) * 128;
;         bf16x8 b0 = *reinterpret_cast<const bf16x8*>(a);
;         bf16x8 b1 = *reinterpret_cast<const bf16x8*>(a + 32 * 256);
;         const bf16x8 qf = qr[d0];
;         p0 = __builtin_amdgcn_mfma_f32_32x32x16_bf16(b0, qf, p0, 0, 0, 0);
;         p1 = __builtin_amdgcn_mfma_f32_32x32x16_bf16(b1, qf, p1, 0, 0, 0); }
.Lh1_noresc:
	v_exp_f32_e32 v66, v228
	v_exp_f32_e32 v67, v229
	v_exp_f32_e32 v68, v230
	v_exp_f32_e32 v69, v231
	v_exp_f32_e32 v70, v232
	v_exp_f32_e32 v71, v233
	v_exp_f32_e32 v72, v234
	v_exp_f32_e32 v73, v235
	v_exp_f32_e32 v74, v236
	v_exp_f32_e32 v75, v237
	v_exp_f32_e32 v76, v238
	v_exp_f32_e32 v77, v239
	v_exp_f32_e32 v78, v98
	v_exp_f32_e32 v79, v99
	v_exp_f32_e32 v80, v100
	v_exp_f32_e32 v81, v101
	s_waitcnt lgkmcnt(0)
	s_barrier
	ds_read_b128 v[230:233], v211 offset:32768
	ds_read_b128 v[234:237], v211 offset:40960
	ds_read_b128 v[238:241], v212 offset:32768
	ds_read_b128 v[242:245], v212 offset:40960
	ds_read_b128 v[162:165], v213 offset:32768
	ds_read_b128 v[166:169], v213 offset:40960
	ds_read_b128 v[170:173], v214 offset:32768
	ds_read_b128 v[174:177], v214 offset:40960
	v_exp_f32_e32 v82, v86
	v_exp_f32_e32 v83, v95
	v_exp_f32_e32 v84, v96
	v_exp_f32_e32 v85, v97
	v_exp_f32_e32 v86, v179
	v_exp_f32_e32 v87, v87
	s_waitcnt lgkmcnt(7)
	v_mfma_f32_32x32x16_bf16 v[114:129], v[230:233], v[158:161], 0
	ds_read_b128 v[230:233], v211 offset:32896
	v_exp_f32_e32 v88, v88
	v_exp_f32_e32 v89, v89
	v_exp_f32_e32 v90, v90
	v_exp_f32_e32 v91, v91
	v_exp_f32_e32 v92, v92
	s_waitcnt lgkmcnt(7)
	v_mfma_f32_32x32x16_bf16 v[98:113], v[234:237], v[158:161], 0
	ds_read_b128 v[234:237], v211 offset:41088
	v_exp_f32_e32 v93, v93
	v_exp_f32_e32 v94, v94
	v_exp_f32_e32 v95, v180
	v_exp_f32_e32 v96, v181
	v_exp_f32_e32 v97, v178
	s_waitcnt lgkmcnt(7)
	v_mfma_f32_32x32x16_bf16 v[114:129], v[238:241], v[154:157], v[114:129]
	ds_read_b128 v[238:241], v212 offset:32896
	v_add_f32_e32 v178, 0, v66
	v_add_f32_e32 v178, v67, v178
	v_add_f32_e32 v178, v68, v178
	v_add_f32_e32 v178, v69, v178
	v_add_f32_e32 v178, v70, v178
	s_waitcnt lgkmcnt(7)
	v_mfma_f32_32x32x16_bf16 v[98:113], v[242:245], v[154:157], v[98:113]
	ds_read_b128 v[242:245], v212 offset:41088
	v_add_f32_e32 v178, v71, v178
	v_add_f32_e32 v178, v72, v178
	v_add_f32_e32 v178, v73, v178
	v_add_f32_e32 v178, v74, v178
	v_add_f32_e32 v178, v75, v178
	s_waitcnt lgkmcnt(7)
	v_mfma_f32_32x32x16_bf16 v[114:129], v[162:165], v[150:153], v[114:129]
	ds_read_b128 v[162:165], v213 offset:32896
	v_add_f32_e32 v178, v76, v178
	v_add_f32_e32 v178, v77, v178
	v_add_f32_e32 v178, v78, v178
	v_add_f32_e32 v178, v79, v178
	s_waitcnt lgkmcnt(7)
	v_mfma_f32_32x32x16_bf16 v[98:113], v[166:169], v[150:153], v[98:113]
	ds_read_b128 v[166:169], v213 offset:41088
	v_add_f32_e32 v178, v80, v178
	v_add_f32_e32 v178, v81, v178
	v_add_f32_e32 v178, v82, v178
	v_add_f32_e32 v178, v83, v178
	s_waitcnt lgkmcnt(7)
	v_mfma_f32_32x32x16_bf16 v[114:129], v[170:173], v[134:137], v[114:129]
	ds_read_b128 v[170:173], v214 offset:32896
	v_add_f32_e32 v178, v84, v178
	v_add_f32_e32 v178, v85, v178
	v_add_f32_e32 v178, v86, v178
	v_add_f32_e32 v178, v87, v178
	s_waitcnt lgkmcnt(7)
	v_mfma_f32_32x32x16_bf16 v[98:113], v[174:177], v[134:137], v[98:113]
	ds_read_b128 v[174:177], v214 offset:41088
	v_add_f32_e32 v178, v88, v178
	v_add_f32_e32 v178, v89, v178
	v_add_f32_e32 v178, v90, v178
	v_add_f32_e32 v178, v91, v178
	s_waitcnt lgkmcnt(7)
	v_mfma_f32_32x32x16_bf16 v[114:129], v[230:233], v[138:141], v[114:129]
	ds_read_b64_tr_b16 v[230:231], v202 offset:0x4000
	ds_read_b64_tr_b16 v[232:233], v202 offset:0x4800
	v_add_f32_e32 v178, v92, v178
	v_add_f32_e32 v178, v93, v178
	v_add_f32_e32 v178, v94, v178
	v_add_f32_e32 v178, v95, v178
	s_waitcnt lgkmcnt(8)
	v_mfma_f32_32x32x16_bf16 v[98:113], v[234:237], v[138:141], v[98:113]
	ds_read_b64_tr_b16 v[234:235], v202 offset:0x5000
	ds_read_b64_tr_b16 v[236:237], v202 offset:0x5800
	v_add_f32_e32 v178, v96, v178
	v_add_f32_e32 v228, v97, v178
	v_mov_b32_e32 v229, v228
	s_nop 1
	v_permlane32_swap_b32_e32 v228, v229
	s_waitcnt lgkmcnt(9)
	v_mfma_f32_32x32x16_bf16 v[114:129], v[238:241], v[142:145], v[114:129]
	ds_read_b64_tr_b16 v[238:239], v202 offset:0x6000
	ds_read_b64_tr_b16 v[240:241], v202 offset:0x6800
	v_cvt_pk_bf16_f32 v178, v66, v67
	v_cvt_pk_bf16_f32 v179, v68, v69
	v_cvt_pk_bf16_f32 v180, v70, v71
	v_cvt_pk_bf16_f32 v181, v72, v73
	s_waitcnt lgkmcnt(10)
	v_mfma_f32_32x32x16_bf16 v[98:113], v[242:245], v[142:145], v[98:113]
	ds_read_b64_tr_b16 v[242:243], v202 offset:0x7000
	ds_read_b64_tr_b16 v[244:245], v202 offset:0x7800
	v_cvt_pk_bf16_f32 v182, v74, v75
	v_cvt_pk_bf16_f32 v183, v76, v77
	v_cvt_pk_bf16_f32 v184, v78, v79
	v_cvt_pk_bf16_f32 v185, v80, v81
	s_waitcnt lgkmcnt(11)
	v_mfma_f32_32x32x16_bf16 v[114:129], v[162:165], v[146:149], v[114:129]
	v_cvt_pk_bf16_f32 v186, v82, v83
	v_cvt_pk_bf16_f32 v187, v84, v85
	v_cvt_pk_bf16_f32 v188, v86, v87
	v_cvt_pk_bf16_f32 v189, v88, v89
	s_waitcnt lgkmcnt(10)
	v_mfma_f32_32x32x16_bf16 v[98:113], v[166:169], v[146:149], v[98:113]
	v_cvt_pk_bf16_f32 v190, v90, v91
	v_cvt_pk_bf16_f32 v191, v92, v93
	v_cvt_pk_bf16_f32 v192, v94, v95
	v_cvt_pk_bf16_f32 v193, v96, v97
	s_waitcnt lgkmcnt(9)
	v_mfma_f32_32x32x16_bf16 v[114:129], v[170:173], v[130:133], v[114:129]
	s_nop 1
	v_permlane32_swap_b32_e32 v178, v180
	v_permlane32_swap_b32_e32 v179, v181
	v_permlane32_swap_b32_e32 v182, v184
	v_permlane32_swap_b32_e32 v183, v185
	s_waitcnt lgkmcnt(8)
	v_mfma_f32_32x32x16_bf16 v[98:113], v[174:177], v[130:133], v[98:113]
	v_permlane32_swap_b32_e32 v186, v188
	v_permlane32_swap_b32_e32 v187, v189
	v_permlane32_swap_b32_e32 v190, v192
	v_permlane32_swap_b32_e32 v191, v193
	s_add_i32 s4, s25, 1
	s_cmp_le_u32 s4, s24
	s_cselect_b64 s[76:77], -1, 0
	s_cmp_gt_u32 s4, s24
	s_cbranch_scc1 .LBB0_1137
	v_add_u32_e32 v84, 0x4000, v255
	v_add_u32_e32 v85, 0x6000, v255
	global_load_dwordx4 v[162:165], v84, s[42:43]
	global_load_dwordx4 v[166:169], v85, s[42:43]
	global_load_dwordx4 v[170:173], v84, s[22:23]
	global_load_dwordx4 v[174:177], v85, s[22:23]
; __device__ __forceinline__ void mask_tile(f32x16& p0, f32x16& p1, int dq, unsigned W) {
;     const float NEG = -__builtin_inff();
; #pragma unroll
;     for (int r = 0; r < 16; ++r) {
;         const int c = (r & 3) + 8 * (r >> 2);
;         if ((unsigned)(dq - c) >= W) p0[r] = NEG;
;         if ((unsigned)(dq - c - 32) >= W) p1[r] = NEG;
;     }
; }
.LBB0_1137:
	s_sub_i32 s27, s26, 63
	s_cmp_le_i32 s26, s13
	s_cselect_b64 s[4:5], -1, 0
	s_cmp_gt_i32 s27, s15
	s_cselect_b64 s[52:53], -1, 0
	s_and_b64 s[4:5], s[4:5], s[52:53]
	s_and_b64 vcc, exec, s[4:5]
	ds_read_b64_tr_b16 v[86:87], v202 offset:0x4200
	ds_read_b64_tr_b16 v[88:89], v202 offset:0x4a00
	ds_read_b64_tr_b16 v[90:91], v202 offset:0x5200
	ds_read_b64_tr_b16 v[92:93], v202 offset:0x5a00
	ds_read_b64_tr_b16 v[94:95], v202 offset:0x6200
	ds_read_b64_tr_b16 v[96:97], v202 offset:0x6a00
	s_cbranch_vccnz .Lh2_nomask
	v_add_u32_e32 v226, s80, v222
	v_add_u32_e32 v66, 0xffffff80, v226
	v_cmp_gt_u32_e32 vcc, s85, v66
	v_add_u32_e32 v66, 0xffffff60, v226
	s_nop 0
	v_cndmask_b32_e32 v114, v215, v114, vcc
	v_cmp_gt_u32_e32 vcc, s85, v66
	v_add_u32_e32 v66, 0xffffff7f, v226
	s_nop 0
	v_cndmask_b32_e32 v98, v215, v98, vcc
	v_cmp_gt_u32_e32 vcc, s85, v66
	v_add_u32_e32 v66, 0xffffff5f, v226
	s_nop 0
	v_cndmask_b32_e32 v115, v215, v115, vcc
	v_cmp_gt_u32_e32 vcc, s85, v66
	v_add_u32_e32 v66, 0xffffff7e, v226
	s_nop 0
	v_cndmask_b32_e32 v99, v215, v99, vcc
	v_cmp_gt_u32_e32 vcc, s85, v66
	v_add_u32_e32 v66, 0xffffff5e, v226
	s_nop 0
	v_cndmask_b32_e32 v116, v215, v116, vcc
	v_cmp_gt_u32_e32 vcc, s85, v66
	v_add_u32_e32 v66, 0xffffff7d, v226
	s_nop 0
	v_cndmask_b32_e32 v100, v215, v100, vcc
	v_cmp_gt_u32_e32 vcc, s85, v66
	v_add_u32_e32 v66, 0xffffff5d, v226
	s_nop 0
	v_cndmask_b32_e32 v117, v215, v117, vcc
	v_cmp_gt_u32_e32 vcc, s85, v66
	v_add_u32_e32 v66, 0xffffff78, v226
	s_nop 0
	v_cndmask_b32_e32 v101, v215, v101, vcc
	v_cmp_gt_u32_e32 vcc, s85, v66
	v_add_u32_e32 v66, 0xffffff58, v226
	s_nop 0
	v_cndmask_b32_e32 v118, v215, v118, vcc
	v_cmp_gt_u32_e32 vcc, s85, v66
	v_add_u32_e32 v66, 0xffffff77, v226
	s_nop 0
	v_cndmask_b32_e32 v102, v215, v102, vcc
	v_cmp_gt_u32_e32 vcc, s85, v66
	v_add_u32_e32 v66, 0xffffff57, v226
	s_nop 0
	v_cndmask_b32_e32 v119, v215, v119, vcc
	v_cmp_gt_u32_e32 vcc, s85, v66
	v_add_u32_e32 v66, 0xffffff76, v226
	s_nop 0
	v_cndmask_b32_e32 v103, v215, v103, vcc
	v_cmp_gt_u32_e32 vcc, s85, v66
	v_add_u32_e32 v66, 0xffffff56, v226
	s_nop 0
	v_cndmask_b32_e32 v120, v215, v120, vcc
	v_cmp_gt_u32_e32 vcc, s85, v66
	v_add_u32_e32 v66, 0xffffff75, v226
	s_nop 0
	v_cndmask_b32_e32 v104, v215, v104, vcc
	v_cmp_gt_u32_e32 vcc, s85, v66
	v_add_u32_e32 v66, 0xffffff55, v226
	s_nop 0
	v_cndmask_b32_e32 v121, v215, v121, vcc
	v_cmp_gt_u32_e32 vcc, s85, v66
	v_add_u32_e32 v66, 0xffffff70, v226
	s_nop 0
	v_cndmask_b32_e32 v105, v215, v105, vcc
	v_cmp_gt_u32_e32 vcc, s85, v66
	v_add_u32_e32 v66, 0xffffff50, v226
	s_nop 0
	v_cndmask_b32_e32 v122, v215, v122, vcc
	v_cmp_gt_u32_e32 vcc, s85, v66
	v_add_u32_e32 v66, 0xffffff6f, v226
	s_nop 0
	v_cndmask_b32_e32 v106, v215, v106, vcc
	v_cmp_gt_u32_e32 vcc, s85, v66
	v_add_u32_e32 v66, 0xffffff4f, v226
	s_nop 0
	v_cndmask_b32_e32 v123, v215, v123, vcc
	v_cmp_gt_u32_e32 vcc, s85, v66
	v_add_u32_e32 v66, 0xffffff6e, v226
	s_nop 0
	v_cndmask_b32_e32 v107, v215, v107, vcc
	v_cmp_gt_u32_e32 vcc, s85, v66
	v_add_u32_e32 v66, 0xffffff4e, v226
	s_nop 0
	v_cndmask_b32_e32 v124, v215, v124, vcc
	v_cmp_gt_u32_e32 vcc, s85, v66
	v_add_u32_e32 v66, 0xffffff6d, v226
	s_nop 0
	v_cndmask_b32_e32 v108, v215, v108, vcc
	v_cmp_gt_u32_e32 vcc, s85, v66
	v_add_u32_e32 v66, 0xffffff4d, v226
	s_nop 0
	v_cndmask_b32_e32 v125, v215, v125, vcc
	v_cmp_gt_u32_e32 vcc, s85, v66
	v_add_u32_e32 v66, 0xffffff68, v226
	s_nop 0
	v_cndmask_b32_e32 v109, v215, v109, vcc
	v_cmp_gt_u32_e32 vcc, s85, v66
	v_add_u32_e32 v66, 0xffffff48, v226
	s_nop 0
	v_cndmask_b32_e32 v126, v215, v126, vcc
	v_cmp_gt_u32_e32 vcc, s85, v66
	v_add_u32_e32 v66, 0xffffff67, v226
	s_nop 0
	v_cndmask_b32_e32 v110, v215, v110, vcc
	v_cmp_gt_u32_e32 vcc, s85, v66
	v_add_u32_e32 v66, 0xffffff47, v226
	s_nop 0
	v_cndmask_b32_e32 v127, v215, v127, vcc
	v_cmp_gt_u32_e32 vcc, s85, v66
	v_add_u32_e32 v66, 0xffffff66, v226
	s_nop 0
	v_cndmask_b32_e32 v111, v215, v111, vcc
	v_cmp_gt_u32_e32 vcc, s85, v66
	v_add_u32_e32 v66, 0xffffff46, v226
	s_nop 0
	v_cndmask_b32_e32 v128, v215, v128, vcc
	v_cmp_gt_u32_e32 vcc, s85, v66
	v_add_u32_e32 v66, 0xffffff65, v226
	s_nop 0
	v_cndmask_b32_e32 v112, v215, v112, vcc
	v_cmp_gt_u32_e32 vcc, s85, v66
	v_add_u32_e32 v66, 0xffffff45, v226
	s_nop 0
	v_cndmask_b32_e32 v129, v215, v129, vcc
	v_cmp_gt_u32_e32 vcc, s85, v66
	s_nop 1
	v_cndmask_b32_e32 v113, v215, v113, vcc
